# saddr+peel plus retention chunk-loop GroupNorm statistics reduced with DPP (quad_perm, row_half_mirror) instead of 3 dependent ds_bpermute round trips
# baseline (speedup 1.0000x reference)
; #define LAS __attribute__((address_space(3)))
; #define LBAR() do { asm volatile("s_waitcnt lgkmcnt(0)" ::: "memory"); __builtin_amdgcn_s_barrier(); asm volatile("" ::: "memory"); } while (0)
; __device__ __forceinline__ unsigned pk2(float lo, float hi) { return pg8::cvt_pk_bf16(lo, hi); }
; __device__ __forceinline__ void retention_unit(LAS unsigned char* lds, const Ptrs& P, int b, int h, int tid) {
;     ...
;             *(LAS v4u*)(Qs + lrow * S72 + lseg * 8) = rq; *(LAS v4u*)(Ks + lrow * S72 + lseg * 8) = rk;
;             v4u k2;
; #pragma unroll
;             for (int t = 0; t < 4; ++t) k2[t] = pk2(bflo(rk[t]) * dkey, bfhi(rk[t]) * dkey);
;             *(LAS v4u*)(K2s + lrow * S72 + lseg * 8) = k2;
;             *(LAS v4u*)(Vs + vrow0 * S144 + vseg * 8) = rv0; *(LAS v4u*)(Vs + (vrow0 + 32) * S144 + vseg * 8) = rv1;
;         }
;         if (n >= 1) {
; #pragma unroll
;             for (int it = 0; it < 4; ++it) sgr[it] = __builtin_nontemporal_load((const v2u*)(gsl + ((size_t)(n - 1) * 64 + 16 * it) * 512));
;         }
;         LBAR();
;         if (n + 1 < 32) { const size_t o4 = (size_t)(n + 1) * 64;
;             rq = __builtin_nontemporal_load((const v4u*)(gq + o4 * 256)); rk = __builtin_nontemporal_load((const v4u*)(gk + o4 * 256)); rv0 = __builtin_nontemporal_load((const v4u*)(gv + o4 * 512)); rv1 = __builtin_nontemporal_load((const v4u*)(gv + (o4 + 32) * 512)); }
;         if (n >= 1) {
;             const int row = tid >> 3, sub = tid & 7;
;             const f32x4 pa = *(const LAS f32x4*)(part + (row * 32 + sub * 4) * 2), pb = *(const LAS f32x4*)(part + (row * 32 + sub * 4) * 2 + 4);
;             float s1 = (pa[0] + pa[2]) + (pb[0] + pb[2]), s2 = (pa[1] + pa[3]) + (pb[1] + pb[3]);
; #pragma unroll
;             for (int x = 1; x < 8; x <<= 1) { s1 += __shfl_xor(s1, x); s2 += __shfl_xor(s2, x); }
;             if (sub == 0) { const float mean = s1 * (1.f / 128.f); float var = s2 * (1.f / 128.f) - mean * mean; var = var < 0.f ? 0.f : var;
;                 stat[row * 2] = mean; stat[row * 2 + 1] = __builtin_amdgcn_rsqf(var + 1e-5f); }
.LBB0_658:
	s_add_i32 s89, s89, 1
	s_bitcmp1_b32 s89, 0
	s_cselect_b32 s18, 0xb400, 0
	s_add_i32 s90, s18, 0
	v_add3_u32 v52, s90, v163, v72
	s_waitcnt vmcnt(3)
	ds_write_b128 v52, v[36:39]
	s_waitcnt vmcnt(2)
	ds_write_b128 v52, v[24:27] offset:9216
	v_lshlrev_b32_e32 v36, 16, v24
	v_and_b32_e32 v37, 0xffff0000, v24
	v_pk_mul_f32 v[36:37], v[102:103], v[36:37]
	v_add_u32_e32 v56, 0, v159
	v_cvt_pk_bf16_f32 v24, v36, v37
	v_lshlrev_b32_e32 v36, 16, v25
	v_and_b32_e32 v37, 0xffff0000, v25
	v_pk_mul_f32 v[36:37], v[102:103], v[36:37]
	v_add_u32_e32 v139, 0x1d400, v56
	v_cvt_pk_bf16_f32 v25, v36, v37
	v_lshlrev_b32_e32 v36, 16, v26
	v_and_b32_e32 v37, 0xffff0000, v26
	v_pk_mul_f32 v[36:37], v[102:103], v[36:37]
	v_and_b32_e32 v60, 64, v131
	v_cvt_pk_bf16_f32 v26, v36, v37
	v_lshlrev_b32_e32 v36, 16, v27
	v_and_b32_e32 v37, 0xffff0000, v27
	v_pk_mul_f32 v[36:37], v[102:103], v[36:37]
	v_add_u32_e32 v60, 64, v60
	v_cvt_pk_bf16_f32 v27, v36, v37
	ds_write_b128 v52, v[24:27] offset:18432
	v_add3_u32 v24, s90, v158, v84
	s_waitcnt vmcnt(1)
	ds_write_b128 v24, v[28:31] offset:27648
	s_waitcnt vmcnt(0)
	ds_write_b128 v24, v[32:35] offset:36864
	v_lshl_add_u64 v[24:25], s[26:27], 0, v[116:117]
	v_add_co_u32_e32 v26, vcc, s58, v24
	v_xor_b32_e32 v61, 1, v131
	s_nop 0
	v_addc_co_u32_e32 v27, vcc, 0, v25, vcc
	v_add_co_u32_e32 v28, vcc, s59, v24
	s_nop 1
	v_addc_co_u32_e32 v29, vcc, 0, v25, vcc
	v_add_co_u32_e32 v30, vcc, s60, v24
	s_nop 1
	v_addc_co_u32_e32 v31, vcc, 0, v25, vcc
	v_add_co_u32_e32 v24, vcc, s61, v24
	s_nop 1
	v_addc_co_u32_e32 v25, vcc, 0, v25, vcc
	global_load_dwordx2 v[54:55], v[26:27], off nt
	global_load_dwordx2 v[52:53], v[28:29], off nt
	global_load_dwordx2 v[122:123], v[30:31], off nt
	global_load_dwordx2 v[118:119], v[24:25], off nt
	v_lshl_add_u64 v[24:25], s[26:27], 0, v[110:111]
	v_add_co_u32_e32 v26, vcc, s62, v24
	v_lshl_add_u64 v[28:29], s[26:27], 0, v[112:113]
	s_nop 0
	v_addc_co_u32_e32 v27, vcc, 0, v25, vcc
	v_add_co_u32_e32 v24, vcc, s63, v24
	s_waitcnt lgkmcnt(0)
	s_barrier
	s_nop 0
	v_addc_co_u32_e32 v25, vcc, 0, v25, vcc
	v_add_co_u32_e32 v30, vcc, s64, v28
	global_load_dwordx4 v[36:39], v[26:27], off nt
	s_nop 0
	global_load_dwordx4 v[24:27], v[24:25], off nt
	v_addc_co_u32_e32 v31, vcc, 0, v29, vcc
	v_add_co_u32_e32 v32, vcc, s65, v28
	s_nop 1
	v_addc_co_u32_e32 v33, vcc, 0, v29, vcc
	global_load_dwordx4 v[28:31], v[30:31], off nt
	s_nop 0
	global_load_dwordx4 v[32:35], v[32:33], off nt
	ds_read_b128 v[56:59], v139
	ds_read_b128 v[184:187], v139 offset:16
	v_cmp_lt_i32_e32 vcc, v61, v60
	s_waitcnt lgkmcnt(1)
	v_pk_add_f32 v[56:57], v[56:57], v[58:59]
	v_cndmask_b32_e32 v61, v131, v61, vcc
	s_waitcnt lgkmcnt(0)
	v_pk_add_f32 v[58:59], v[184:185], v[186:187]
	v_lshlrev_b32_e32 v138, 2, v61
	v_pk_add_f32 v[56:57], v[56:57], v[58:59]
	s_nop 1
	v_add_f32_dpp v56, v56, v56 quad_perm:[1,0,3,2] row_mask:0xf bank_mask:0xf
	v_add_f32_dpp v57, v57, v57 quad_perm:[1,0,3,2] row_mask:0xf bank_mask:0xf
	v_xor_b32_e32 v61, 2, v131
	v_cmp_lt_i32_e32 vcc, v61, v60
	s_nop 1
	v_cndmask_b32_e32 v61, v131, v61, vcc
	v_lshlrev_b32_e32 v140, 2, v61
	v_add_f32_dpp v56, v56, v56 quad_perm:[2,3,0,1] row_mask:0xf bank_mask:0xf
	v_add_f32_dpp v57, v57, v57 quad_perm:[2,3,0,1] row_mask:0xf bank_mask:0xf
	v_xor_b32_e32 v58, 4, v131
	v_cmp_lt_i32_e32 vcc, v58, v60
	s_nop 1
	v_cndmask_b32_e32 v58, v131, v58, vcc
	v_lshlrev_b32_e32 v141, 2, v58
	v_add_f32_dpp v56, v56, v56 row_half_mirror row_mask:0xf bank_mask:0xf
	v_add_f32_dpp v57, v57, v57 row_half_mirror row_mask:0xf bank_mask:0xf
	s_and_saveexec_b64 s[18:19], s[0:1]
	s_cbranch_execz .LBB0_657
	s_waitcnt lgkmcnt(0)
	v_add_u32_e32 v58, 0, v198
	v_pk_mul_f32 v[56:57], v[56:57], s[6:7] op_sel_hi:[1,0]
	v_add_u32_e32 v58, 0x21400, v58
	v_fma_f32 v57, -v56, v56, v57
	v_cmp_ngt_f32_e32 vcc, 0, v57
	s_nop 1
	v_cndmask_b32_e32 v57, 0, v57, vcc
	v_add_f32_e32 v57, 0x3727c5ac, v57
	v_rsq_f32_e32 v57, v57
	ds_write2_b32 v58, v56, v57 offset1:1
	s_branch .LBB0_657
